# phase 0: non-temporal hint on the read-once f32 input and FFN0 weight loads as well
# speedup vs baseline: 1.0108x; 1.0058x over previous
.LBB0_1035:
	s_mul_hi_i32 s6, s0, 0x2e8ba2e9
	s_lshr_b32 s7, s6, 31
	s_ashr_i32 s6, s6, 4
	s_add_i32 s6, s6, s7
	s_mul_i32 s7, s6, 0xffffffa8
	s_add_i32 s7, s0, s7
	s_mul_i32 s8, s7, 47
	s_sext_i32_i16 s9, s8
	s_ashr_i32 s12, s9, 11
	s_bfe_u32 s8, s8, 0x1000f
	s_add_i32 s12, s12, s8
	s_mul_i32 s8, s12, 44
	s_sub_i32 s8, s7, s8
	s_sext_i32_i8 s13, s8
	s_lshl_b32 s8, s13, 6
	s_add_i32 s7, s7, 43
	s_cmpk_lt_u32 s7, 0x57
	s_cselect_b32 s7, s75, s77
	s_cselect_b32 s14, s74, s76
	s_ashr_i32 s9, s8, 31
	s_lshl_b32 s6, s6, 6
	s_lshl_b64 s[10:11], s[8:9], 2
	s_add_u32 s10, s14, s10
	v_or_b32_e32 v70, s6, v66
	s_addc_u32 s11, s7, s11
	v_lshl_add_u64 v[2:3], s[10:11], 0, v[0:1]
	v_or_b32_e32 v6, 4, v70
	v_mad_i64_i32 v[4:5], s[10:11], v70, s67, v[2:3]
	v_mad_i64_i32 v[6:7], s[10:11], v6, s67, v[2:3]
	global_load_dwordx4 v[62:65], v[4:5], off nt
	global_load_dwordx4 v[58:61], v[6:7], off nt
	v_or_b32_e32 v4, 8, v70
	v_or_b32_e32 v6, 12, v70
	v_mad_i64_i32 v[4:5], s[10:11], v4, s67, v[2:3]
	v_mad_i64_i32 v[6:7], s[10:11], v6, s67, v[2:3]
	global_load_dwordx4 v[54:57], v[4:5], off nt
	global_load_dwordx4 v[50:53], v[6:7], off nt
	v_or_b32_e32 v4, 16, v70
	v_or_b32_e32 v6, 20, v70
	v_mad_i64_i32 v[4:5], s[10:11], v4, s67, v[2:3]
	v_mad_i64_i32 v[6:7], s[10:11], v6, s67, v[2:3]
	global_load_dwordx4 v[46:49], v[4:5], off nt
	global_load_dwordx4 v[42:45], v[6:7], off nt
	v_or_b32_e32 v4, 24, v70
	v_or_b32_e32 v6, 28, v70
	v_mad_i64_i32 v[4:5], s[10:11], v4, s67, v[2:3]
	v_mad_i64_i32 v[6:7], s[10:11], v6, s67, v[2:3]
	global_load_dwordx4 v[38:41], v[4:5], off nt
	global_load_dwordx4 v[34:37], v[6:7], off nt
	v_or_b32_e32 v4, 32, v70
	v_or_b32_e32 v6, 36, v70
	v_mad_i64_i32 v[4:5], s[10:11], v4, s67, v[2:3]
	v_mad_i64_i32 v[6:7], s[10:11], v6, s67, v[2:3]
	global_load_dwordx4 v[30:33], v[4:5], off nt
	global_load_dwordx4 v[26:29], v[6:7], off nt
	v_or_b32_e32 v4, 40, v70
	v_or_b32_e32 v6, 44, v70
	v_mad_i64_i32 v[4:5], s[10:11], v4, s67, v[2:3]
	v_mad_i64_i32 v[6:7], s[10:11], v6, s67, v[2:3]
	global_load_dwordx4 v[22:25], v[4:5], off nt
	global_load_dwordx4 v[18:21], v[6:7], off nt
	v_or_b32_e32 v4, 48, v70
	v_or_b32_e32 v6, 52, v70
	v_or_b32_e32 v8, 56, v70
	v_or_b32_e32 v10, 60, v70
	v_mad_i64_i32 v[4:5], s[10:11], v4, s67, v[2:3]
	v_mad_i64_i32 v[6:7], s[10:11], v6, s67, v[2:3]
	v_mad_i64_i32 v[8:9], s[10:11], v8, s67, v[2:3]
	v_mad_i64_i32 v[2:3], s[10:11], v10, s67, v[2:3]
	global_load_dwordx4 v[14:17], v[4:5], off nt
	global_load_dwordx4 v[10:13], v[6:7], off nt
	s_nop 0
	global_load_dwordx4 v[6:9], v[8:9], off nt
	s_nop 0
	global_load_dwordx4 v[2:5], v[2:3], off nt
	v_cndmask_b32_e64 v71, 0, 1, s[24:25]
	v_cmp_ne_u32_e64 s[36:37], 1, v71
	s_andn2_b64 vcc, exec, s[24:25]
	s_cbranch_vccnz .LBB0_1058
	v_ashrrev_i32_e32 v71, 31, v70
	v_lshl_add_u64 v[70:71], v[70:71], 2, s[72:73]
	s_ashr_i32 s7, s6, 31
	global_load_dword v122, v[70:71], off
	global_load_dword v123, v[70:71], off offset:16
	global_load_dword v124, v[70:71], off offset:32
	global_load_dword v125, v[70:71], off offset:48
	global_load_dword v126, v[70:71], off offset:64
	global_load_dword v127, v[70:71], off offset:80
	global_load_dword v128, v[70:71], off offset:96
	global_load_dword v129, v[70:71], off offset:112
	global_load_dword v130, v[70:71], off offset:128
	global_load_dword v131, v[70:71], off offset:144
	global_load_dword v132, v[70:71], off offset:160
	global_load_dword v133, v[70:71], off offset:176
	global_load_dword v134, v[70:71], off offset:192
	global_load_dword v135, v[70:71], off offset:208
	global_load_dword v136, v[70:71], off offset:224
	global_load_dword v137, v[70:71], off offset:240
	v_lshl_add_u64 v[70:71], s[6:7], 0, v[66:67]
	v_lshl_add_u64 v[70:71], v[70:71], 2, s[72:73]
	s_waitcnt vmcnt(0)
	v_mov_b32_e32 v86, v122
	v_mov_b32_e32 v70, v123
	v_pk_mul_f32 v[88:89], v[62:63], v[86:87] op_sel_hi:[1,0]
	v_pk_mul_f32 v[86:87], v[64:65], v[86:87] op_sel_hi:[1,0]
	ds_write2_b32 v83, v88, v89 offset1:1
	ds_write2_b32 v83, v86, v87 offset0:2 offset1:3
	s_cbranch_execnz .LBB0_1038

.LBB0_1156:
	s_ashr_i32 s3, s2, 31
	s_lshl_b64 s[4:5], s[2:3], 12
	s_waitcnt lgkmcnt(0)
	v_lshl_add_u64 v[2:3], v[34:35], 0, s[4:5]
	global_load_dwordx4 v[30:33], v[2:3], off nt
	global_load_dwordx4 v[26:29], v[2:3], off offset:1024 nt
	global_load_dwordx4 v[22:25], v[2:3], off offset:2048 nt
	global_load_dwordx4 v[18:21], v[2:3], off offset:3072 nt
	s_add_i32 s4, s2, s33
	s_cmpk_lt_i32 s4, 0x4000
	s_cselect_b64 s[6:7], -1, 0
	s_ashr_i32 s5, s4, 31
	s_lshl_b64 s[8:9], s[4:5], 12
	s_cmpk_gt_i32 s4, 0x3fff
	v_lshl_add_u64 v[40:41], v[34:35], 0, s[8:9]
	v_mov_b32_e32 v2, 0
	v_mov_b32_e32 v6, 0
	v_mov_b32_e32 v7, 0
	v_mov_b32_e32 v8, 0
	v_mov_b32_e32 v9, 0
	s_cbranch_scc1 .LBB0_1158
	global_load_dwordx4 v[6:9], v[40:41], off nt
.LBB0_1158:
	v_cndmask_b32_e64 v3, 0, 1, s[6:7]
	v_cmp_ne_u32_e64 s[38:39], 1, v3
	s_andn2_b64 vcc, exec, s[6:7]
	v_mov_b32_e32 v3, 0
	v_mov_b32_e32 v4, 0
	v_mov_b32_e32 v5, 0
	s_cbranch_vccnz .LBB0_1160
	global_load_dwordx4 v[2:5], v[40:41], off offset:1024 nt
.LBB0_1160:
	v_mov_b32_e32 v10, 0
	s_and_b64 vcc, exec, s[38:39]
	v_mov_b32_e32 v14, 0
	v_mov_b32_e32 v15, 0
	v_mov_b32_e32 v16, 0
	v_mov_b32_e32 v17, 0
	s_cbranch_vccnz .LBB0_1162
	global_load_dwordx4 v[14:17], v[40:41], off offset:2048 nt
.LBB0_1162:
	s_and_b64 vcc, exec, s[38:39]
	v_mov_b32_e32 v11, 0
	v_mov_b32_e32 v12, 0
	v_mov_b32_e32 v13, 0
	s_cbranch_vccnz .LBB0_1164
	global_load_dwordx4 v[10:13], v[40:41], off offset:3072 nt
